# line-coalesced residual epilogue (accumulator tiles turned around per wave in LDS, 8 lanes per 128-byte token row) for the first residual GEMM site
# speedup vs baseline: 1.0592x; 1.0129x over previous
.LBB0_46:
	v_and_b32_e32 v101, 7, v131
	v_bfe_u32 v100, v131, 3, 3
	v_lshrrev_b32_e32 v0, 6, v131
	v_mul_u32_u24_e32 v0, 0x2400, v0
	v_add_u32_e32 v0, 0xa000, v0
	v_and_b32_e32 v98, 31, v131
	v_mul_u32_u24_e32 v98, 0x90, v98
	v_bfe_u32 v99, v131, 5, 1
	v_lshl_add_u32 v98, v99, 4, v98
	v_add_u32_e32 v98, v98, v0
	v_mul_u32_u24_e32 v99, 0x90, v100
	v_lshl_add_u32 v99, v101, 4, v99
	v_add_u32_e32 v99, v99, v0
	s_lshl_b32 s20, s61, 7
	v_and_b32_e32 v0, 64, v114
	v_lshl_add_u32 v101, v101, 2, v0
	v_add_u32_e32 v101, s20, v101
	v_lshlrev_b32_e32 v101, 2, v101
	s_mul_i32 s20, s60, 0xc0
	v_add3_u32 v102, s20, v113, v100
	v_mov_b32_e32 v0, v101
	v_lshl_add_u64 v[116:117], s[14:15], 0, v[0:1]
	s_and_b64 vcc, exec, s[54:55]
	s_cbranch_vccz .Lrt_a_nong
	global_load_dwordx4 v[122:125], v[116:117], off
	global_load_dwordx4 v[126:129], v[116:117], off offset:128
.Lrt_a_nong:
	ds_write_b128 v98, v[82:85] offset:0
	ds_write_b128 v98, v[86:89] offset:32
	ds_write_b128 v98, v[90:93] offset:64
	ds_write_b128 v98, v[94:97] offset:96
	ds_read_b128 v[180:183], v99 offset:0
	ds_read_b128 v[184:187], v99 offset:1152
	ds_read_b128 v[188:191], v99 offset:2304
	ds_read_b128 v[192:195], v99 offset:3456
	v_add_u32_e32 v115, 0, v102
	v_subrev_co_u32_e32 v103, vcc, 0x1000, v115
	v_lshrrev_b32_e32 v103, 11, v103
	v_add_u32_e32 v103, 1, v103
	s_nop 0
	v_cndmask_b32_e64 v103, v103, 0, vcc
	v_add_u32_e32 v0, s48, v103
	v_mul_u32_u24_e32 v0, 0x6000, v0
	v_add_u32_e32 v0, v0, v101
	v_lshl_add_u64 v[116:117], s[50:51], 0, v[0:1]
	global_load_dwordx4 v[212:215], v[116:117], off offset:0
	v_lshlrev_b32_e32 v0, 12, v115
	v_add_u32_e32 v0, v0, v101
	v_lshl_add_u64 v[104:105], s[6:7], 0, v[0:1]
	global_load_dwordx4 v[196:199], v[104:105], off offset:0
	s_and_b64 vcc, exec, s[54:55]
	s_cbranch_vccz .Lrt_a_a_0_0_0
	v_add_u32_e32 v0, s52, v103
	v_mul_u32_u24_e32 v0, 0x6000, v0
	v_add_u32_e32 v0, v0, v101
	v_lshl_add_u64 v[116:117], s[46:47], 0, v[0:1]
	global_load_dwordx4 v[138:141], v[116:117], off offset:0
.Lrt_a_a_0_0_0:
	v_add_u32_e32 v115, 8, v102
	v_subrev_co_u32_e32 v103, vcc, 0x1000, v115
	v_lshrrev_b32_e32 v103, 11, v103
	v_add_u32_e32 v103, 1, v103
	s_nop 0
	v_cndmask_b32_e64 v103, v103, 0, vcc
	v_add_u32_e32 v0, s48, v103
	v_mul_u32_u24_e32 v0, 0x6000, v0
	v_add_u32_e32 v0, v0, v101
	v_lshl_add_u64 v[116:117], s[50:51], 0, v[0:1]
	global_load_dwordx4 v[216:219], v[116:117], off offset:0
	v_lshlrev_b32_e32 v0, 12, v115
	v_add_u32_e32 v0, v0, v101
	v_lshl_add_u64 v[106:107], s[6:7], 0, v[0:1]
	global_load_dwordx4 v[200:203], v[106:107], off offset:0
	s_and_b64 vcc, exec, s[54:55]
	s_cbranch_vccz .Lrt_a_a_0_0_1
	v_add_u32_e32 v0, s52, v103
	v_mul_u32_u24_e32 v0, 0x6000, v0
	v_add_u32_e32 v0, v0, v101
	v_lshl_add_u64 v[116:117], s[46:47], 0, v[0:1]
	global_load_dwordx4 v[142:145], v[116:117], off offset:0
.Lrt_a_a_0_0_1:
	v_add_u32_e32 v115, 16, v102
	v_subrev_co_u32_e32 v103, vcc, 0x1000, v115
	v_lshrrev_b32_e32 v103, 11, v103
	v_add_u32_e32 v103, 1, v103
	s_nop 0
	v_cndmask_b32_e64 v103, v103, 0, vcc
	v_add_u32_e32 v0, s48, v103
	v_mul_u32_u24_e32 v0, 0x6000, v0
	v_add_u32_e32 v0, v0, v101
	v_lshl_add_u64 v[116:117], s[50:51], 0, v[0:1]
	global_load_dwordx4 v[220:223], v[116:117], off offset:0
	v_lshlrev_b32_e32 v0, 12, v115
	v_add_u32_e32 v0, v0, v101
	v_lshl_add_u64 v[108:109], s[6:7], 0, v[0:1]
	global_load_dwordx4 v[204:207], v[108:109], off offset:0
	s_and_b64 vcc, exec, s[54:55]
	s_cbranch_vccz .Lrt_a_a_0_0_2
	v_add_u32_e32 v0, s52, v103
	v_mul_u32_u24_e32 v0, 0x6000, v0
	v_add_u32_e32 v0, v0, v101
	v_lshl_add_u64 v[116:117], s[46:47], 0, v[0:1]
	global_load_dwordx4 v[146:149], v[116:117], off offset:0
.Lrt_a_a_0_0_2:
	v_add_u32_e32 v115, 24, v102
	v_subrev_co_u32_e32 v103, vcc, 0x1000, v115
	v_lshrrev_b32_e32 v103, 11, v103
	v_add_u32_e32 v103, 1, v103
	s_nop 0
	v_cndmask_b32_e64 v103, v103, 0, vcc
	v_add_u32_e32 v0, s48, v103
	v_mul_u32_u24_e32 v0, 0x6000, v0
	v_add_u32_e32 v0, v0, v101
	v_lshl_add_u64 v[116:117], s[50:51], 0, v[0:1]
	global_load_dwordx4 v[134:137], v[116:117], off offset:0
	v_lshlrev_b32_e32 v0, 12, v115
	v_add_u32_e32 v0, v0, v101
	v_lshl_add_u64 v[110:111], s[6:7], 0, v[0:1]
	global_load_dwordx4 v[208:211], v[110:111], off offset:0
	s_and_b64 vcc, exec, s[54:55]
	s_cbranch_vccz .Lrt_a_a_0_0_3
	v_add_u32_e32 v0, s52, v103
	v_mul_u32_u24_e32 v0, 0x6000, v0
	v_add_u32_e32 v0, v0, v101
	v_lshl_add_u64 v[116:117], s[46:47], 0, v[0:1]
	global_load_dwordx4 v[118:121], v[116:117], off offset:0
.Lrt_a_a_0_0_3:
	s_waitcnt vmcnt(0) lgkmcnt(0)
	v_pk_fma_f32 v[196:197], v[180:181], v[212:213], v[196:197]
	v_pk_fma_f32 v[198:199], v[182:183], v[214:215], v[198:199]
	v_pk_fma_f32 v[200:201], v[184:185], v[216:217], v[200:201]
	v_pk_fma_f32 v[202:203], v[186:187], v[218:219], v[202:203]
	v_pk_fma_f32 v[204:205], v[188:189], v[220:221], v[204:205]
	v_pk_fma_f32 v[206:207], v[190:191], v[222:223], v[206:207]
	v_pk_fma_f32 v[208:209], v[192:193], v[134:135], v[208:209]
	v_pk_fma_f32 v[210:211], v[194:195], v[136:137], v[210:211]
	global_store_dwordx4 v[104:105], v[196:199], off offset:0
	global_store_dwordx4 v[106:107], v[200:203], off offset:0
	global_store_dwordx4 v[108:109], v[204:207], off offset:0
	global_store_dwordx4 v[110:111], v[208:211], off offset:0
	s_and_b64 vcc, exec, s[54:55]
	s_cbranch_vccz .Lrt_a_x_0_0
	v_mul_f32_e32 v180, v196, v196
	v_fmac_f32_e32 v180, v197, v197
	v_fmac_f32_e32 v180, v198, v198
	v_fmac_f32_e32 v180, v199, v199
	v_pk_add_f32 v[138:139], v[138:139], 1.0 op_sel_hi:[1,0]
	v_pk_add_f32 v[140:141], v[140:141], 1.0 op_sel_hi:[1,0]
	v_pk_mul_f32 v[196:197], v[196:197], v[122:123]
	v_pk_mul_f32 v[198:199], v[198:199], v[124:125]
	v_pk_mul_f32 v[196:197], v[196:197], v[138:139]
	v_pk_mul_f32 v[198:199], v[198:199], v[140:141]
	v_cvt_pk_f16_f32 v196, v196, v197
	v_cvt_pk_f16_f32 v197, v198, v199
	v_add_u32_e32 v115, 0, v102
	v_lshlrev_b32_e32 v0, 12, v115
	v_add_u32_e32 v0, v0, v101
	v_lshrrev_b32_e32 v0, 1, v0
	v_lshl_add_u64 v[116:117], s[8:9], 0, v[0:1]
	global_store_dwordx2 v[116:117], v[196:197], off offset:0
	v_mul_f32_e32 v184, v200, v200
	v_fmac_f32_e32 v184, v201, v201
	v_fmac_f32_e32 v184, v202, v202
	v_fmac_f32_e32 v184, v203, v203
	v_pk_add_f32 v[142:143], v[142:143], 1.0 op_sel_hi:[1,0]
	v_pk_add_f32 v[144:145], v[144:145], 1.0 op_sel_hi:[1,0]
	v_pk_mul_f32 v[200:201], v[200:201], v[122:123]
	v_pk_mul_f32 v[202:203], v[202:203], v[124:125]
	v_pk_mul_f32 v[200:201], v[200:201], v[142:143]
	v_pk_mul_f32 v[202:203], v[202:203], v[144:145]
	v_cvt_pk_f16_f32 v200, v200, v201
	v_cvt_pk_f16_f32 v201, v202, v203
	v_add_u32_e32 v115, 8, v102
	v_lshlrev_b32_e32 v0, 12, v115
	v_add_u32_e32 v0, v0, v101
	v_lshrrev_b32_e32 v0, 1, v0
	v_lshl_add_u64 v[116:117], s[8:9], 0, v[0:1]
	global_store_dwordx2 v[116:117], v[200:201], off offset:0
	v_mul_f32_e32 v188, v204, v204
	v_fmac_f32_e32 v188, v205, v205
	v_fmac_f32_e32 v188, v206, v206
	v_fmac_f32_e32 v188, v207, v207
	v_pk_add_f32 v[146:147], v[146:147], 1.0 op_sel_hi:[1,0]
	v_pk_add_f32 v[148:149], v[148:149], 1.0 op_sel_hi:[1,0]
	v_pk_mul_f32 v[204:205], v[204:205], v[122:123]
	v_pk_mul_f32 v[206:207], v[206:207], v[124:125]
	v_pk_mul_f32 v[204:205], v[204:205], v[146:147]
	v_pk_mul_f32 v[206:207], v[206:207], v[148:149]
	v_cvt_pk_f16_f32 v204, v204, v205
	v_cvt_pk_f16_f32 v205, v206, v207
	v_add_u32_e32 v115, 16, v102
	v_lshlrev_b32_e32 v0, 12, v115
	v_add_u32_e32 v0, v0, v101
	v_lshrrev_b32_e32 v0, 1, v0
	v_lshl_add_u64 v[116:117], s[8:9], 0, v[0:1]
	global_store_dwordx2 v[116:117], v[204:205], off offset:0
	v_mul_f32_e32 v192, v208, v208
	v_fmac_f32_e32 v192, v209, v209
	v_fmac_f32_e32 v192, v210, v210
	v_fmac_f32_e32 v192, v211, v211
	v_pk_add_f32 v[118:119], v[118:119], 1.0 op_sel_hi:[1,0]
	v_pk_add_f32 v[120:121], v[120:121], 1.0 op_sel_hi:[1,0]
	v_pk_mul_f32 v[208:209], v[208:209], v[122:123]
	v_pk_mul_f32 v[210:211], v[210:211], v[124:125]
	v_pk_mul_f32 v[208:209], v[208:209], v[118:119]
	v_pk_mul_f32 v[210:211], v[210:211], v[120:121]
	v_cvt_pk_f16_f32 v208, v208, v209
	v_cvt_pk_f16_f32 v209, v210, v211
	v_add_u32_e32 v115, 24, v102
	v_lshlrev_b32_e32 v0, 12, v115
	v_add_u32_e32 v0, v0, v101
	v_lshrrev_b32_e32 v0, 1, v0
	v_lshl_add_u64 v[116:117], s[8:9], 0, v[0:1]
	global_store_dwordx2 v[116:117], v[208:209], off offset:0
	s_nop 1
	v_add_f32_dpp v180, v180, v180 quad_perm:[1,0,3,2] row_mask:0xf bank_mask:0xf bound_ctrl:1
	v_add_f32_dpp v184, v184, v184 quad_perm:[1,0,3,2] row_mask:0xf bank_mask:0xf bound_ctrl:1
	v_add_f32_dpp v188, v188, v188 quad_perm:[1,0,3,2] row_mask:0xf bank_mask:0xf bound_ctrl:1
	v_add_f32_dpp v192, v192, v192 quad_perm:[1,0,3,2] row_mask:0xf bank_mask:0xf bound_ctrl:1
	s_nop 1
	v_add_f32_dpp v180, v180, v180 quad_perm:[2,3,0,1] row_mask:0xf bank_mask:0xf bound_ctrl:1
	v_add_f32_dpp v184, v184, v184 quad_perm:[2,3,0,1] row_mask:0xf bank_mask:0xf bound_ctrl:1
	v_add_f32_dpp v188, v188, v188 quad_perm:[2,3,0,1] row_mask:0xf bank_mask:0xf bound_ctrl:1
	v_add_f32_dpp v192, v192, v192 quad_perm:[2,3,0,1] row_mask:0xf bank_mask:0xf bound_ctrl:1
	s_nop 1
	v_add_f32_dpp v180, v180, v180 row_half_mirror row_mask:0xf bank_mask:0xf bound_ctrl:1
	v_add_f32_dpp v184, v184, v184 row_half_mirror row_mask:0xf bank_mask:0xf bound_ctrl:1
	v_add_f32_dpp v188, v188, v188 row_half_mirror row_mask:0xf bank_mask:0xf bound_ctrl:1
	v_add_f32_dpp v192, v192, v192 row_half_mirror row_mask:0xf bank_mask:0xf bound_ctrl:1
	s_mov_b64 s[42:43], exec
	s_mov_b32 s20, 0x01010101
	s_mov_b32 exec_lo, s20
	s_mov_b32 exec_hi, s20
	v_add_u32_e32 v0, 0, v102
	v_lshlrev_b32_e32 v0, 2, v0
	v_lshl_add_u64 v[116:117], s[12:13], 0, v[0:1]
	global_atomic_add_f32 v[116:117], v180, off
	v_add_u32_e32 v0, 8, v102
	v_lshlrev_b32_e32 v0, 2, v0
	v_lshl_add_u64 v[116:117], s[12:13], 0, v[0:1]
	global_atomic_add_f32 v[116:117], v184, off
	v_add_u32_e32 v0, 16, v102
	v_lshlrev_b32_e32 v0, 2, v0
	v_lshl_add_u64 v[116:117], s[12:13], 0, v[0:1]
	global_atomic_add_f32 v[116:117], v188, off
	v_add_u32_e32 v0, 24, v102
	v_lshlrev_b32_e32 v0, 2, v0
	v_lshl_add_u64 v[116:117], s[12:13], 0, v[0:1]
	global_atomic_add_f32 v[116:117], v192, off
	s_mov_b64 exec, s[42:43]
.Lrt_a_x_0_0:
	ds_write_b128 v98, v[66:69] offset:4608
	ds_write_b128 v98, v[70:73] offset:4640
	ds_write_b128 v98, v[74:77] offset:4672
	ds_write_b128 v98, v[78:81] offset:4704
	ds_read_b128 v[180:183], v99 offset:4608
	ds_read_b128 v[184:187], v99 offset:5760
	ds_read_b128 v[188:191], v99 offset:6912
	ds_read_b128 v[192:195], v99 offset:8064
	v_add_u32_e32 v115, 0, v102
	v_subrev_co_u32_e32 v103, vcc, 0x1000, v115
	v_lshrrev_b32_e32 v103, 11, v103
	v_add_u32_e32 v103, 1, v103
	s_nop 0
	v_cndmask_b32_e64 v103, v103, 0, vcc
	v_add_u32_e32 v0, s48, v103
	v_mul_u32_u24_e32 v0, 0x6000, v0
	v_add_u32_e32 v0, v0, v101
	v_lshl_add_u64 v[116:117], s[50:51], 0, v[0:1]
	global_load_dwordx4 v[212:215], v[116:117], off offset:128
	v_lshlrev_b32_e32 v0, 12, v115
	v_add_u32_e32 v0, v0, v101
	v_lshl_add_u64 v[104:105], s[6:7], 0, v[0:1]
	global_load_dwordx4 v[196:199], v[104:105], off offset:128
	s_and_b64 vcc, exec, s[54:55]
	s_cbranch_vccz .Lrt_a_a_0_1_0
	v_add_u32_e32 v0, s52, v103
	v_mul_u32_u24_e32 v0, 0x6000, v0
	v_add_u32_e32 v0, v0, v101
	v_lshl_add_u64 v[116:117], s[46:47], 0, v[0:1]
	global_load_dwordx4 v[138:141], v[116:117], off offset:128
.Lrt_a_a_0_1_0:
	v_add_u32_e32 v115, 8, v102
	v_subrev_co_u32_e32 v103, vcc, 0x1000, v115
	v_lshrrev_b32_e32 v103, 11, v103
	v_add_u32_e32 v103, 1, v103
	s_nop 0
	v_cndmask_b32_e64 v103, v103, 0, vcc
	v_add_u32_e32 v0, s48, v103
	v_mul_u32_u24_e32 v0, 0x6000, v0
	v_add_u32_e32 v0, v0, v101
	v_lshl_add_u64 v[116:117], s[50:51], 0, v[0:1]
	global_load_dwordx4 v[216:219], v[116:117], off offset:128
	v_lshlrev_b32_e32 v0, 12, v115
	v_add_u32_e32 v0, v0, v101
	v_lshl_add_u64 v[106:107], s[6:7], 0, v[0:1]
	global_load_dwordx4 v[200:203], v[106:107], off offset:128
	s_and_b64 vcc, exec, s[54:55]
	s_cbranch_vccz .Lrt_a_a_0_1_1
	v_add_u32_e32 v0, s52, v103
	v_mul_u32_u24_e32 v0, 0x6000, v0
	v_add_u32_e32 v0, v0, v101
	v_lshl_add_u64 v[116:117], s[46:47], 0, v[0:1]
	global_load_dwordx4 v[142:145], v[116:117], off offset:128
.Lrt_a_a_0_1_1:
	v_add_u32_e32 v115, 16, v102
	v_subrev_co_u32_e32 v103, vcc, 0x1000, v115
	v_lshrrev_b32_e32 v103, 11, v103
	v_add_u32_e32 v103, 1, v103
	s_nop 0
	v_cndmask_b32_e64 v103, v103, 0, vcc
	v_add_u32_e32 v0, s48, v103
	v_mul_u32_u24_e32 v0, 0x6000, v0
	v_add_u32_e32 v0, v0, v101
	v_lshl_add_u64 v[116:117], s[50:51], 0, v[0:1]
	global_load_dwordx4 v[220:223], v[116:117], off offset:128
	v_lshlrev_b32_e32 v0, 12, v115
	v_add_u32_e32 v0, v0, v101
	v_lshl_add_u64 v[108:109], s[6:7], 0, v[0:1]
	global_load_dwordx4 v[204:207], v[108:109], off offset:128
	s_and_b64 vcc, exec, s[54:55]
	s_cbranch_vccz .Lrt_a_a_0_1_2
	v_add_u32_e32 v0, s52, v103
	v_mul_u32_u24_e32 v0, 0x6000, v0
	v_add_u32_e32 v0, v0, v101
	v_lshl_add_u64 v[116:117], s[46:47], 0, v[0:1]
	global_load_dwordx4 v[146:149], v[116:117], off offset:128
.Lrt_a_a_0_1_2:
	v_add_u32_e32 v115, 24, v102
	v_subrev_co_u32_e32 v103, vcc, 0x1000, v115
	v_lshrrev_b32_e32 v103, 11, v103
	v_add_u32_e32 v103, 1, v103
	s_nop 0
	v_cndmask_b32_e64 v103, v103, 0, vcc
	v_add_u32_e32 v0, s48, v103
	v_mul_u32_u24_e32 v0, 0x6000, v0
	v_add_u32_e32 v0, v0, v101
	v_lshl_add_u64 v[116:117], s[50:51], 0, v[0:1]
	global_load_dwordx4 v[134:137], v[116:117], off offset:128
	v_lshlrev_b32_e32 v0, 12, v115
	v_add_u32_e32 v0, v0, v101
	v_lshl_add_u64 v[110:111], s[6:7], 0, v[0:1]
	global_load_dwordx4 v[208:211], v[110:111], off offset:128
	s_and_b64 vcc, exec, s[54:55]
	s_cbranch_vccz .Lrt_a_a_0_1_3
	v_add_u32_e32 v0, s52, v103
	v_mul_u32_u24_e32 v0, 0x6000, v0
	v_add_u32_e32 v0, v0, v101
	v_lshl_add_u64 v[116:117], s[46:47], 0, v[0:1]
	global_load_dwordx4 v[118:121], v[116:117], off offset:128
.Lrt_a_a_0_1_3:
	s_waitcnt vmcnt(0) lgkmcnt(0)
	v_pk_fma_f32 v[196:197], v[180:181], v[212:213], v[196:197]
	v_pk_fma_f32 v[198:199], v[182:183], v[214:215], v[198:199]
	v_pk_fma_f32 v[200:201], v[184:185], v[216:217], v[200:201]
	v_pk_fma_f32 v[202:203], v[186:187], v[218:219], v[202:203]
	v_pk_fma_f32 v[204:205], v[188:189], v[220:221], v[204:205]
	v_pk_fma_f32 v[206:207], v[190:191], v[222:223], v[206:207]
	v_pk_fma_f32 v[208:209], v[192:193], v[134:135], v[208:209]
	v_pk_fma_f32 v[210:211], v[194:195], v[136:137], v[210:211]
	global_store_dwordx4 v[104:105], v[196:199], off offset:128
	global_store_dwordx4 v[106:107], v[200:203], off offset:128
	global_store_dwordx4 v[108:109], v[204:207], off offset:128
	global_store_dwordx4 v[110:111], v[208:211], off offset:128
	s_and_b64 vcc, exec, s[54:55]
	s_cbranch_vccz .Lrt_a_x_0_1
	v_mul_f32_e32 v180, v196, v196
	v_fmac_f32_e32 v180, v197, v197
	v_fmac_f32_e32 v180, v198, v198
	v_fmac_f32_e32 v180, v199, v199
	v_pk_add_f32 v[138:139], v[138:139], 1.0 op_sel_hi:[1,0]
	v_pk_add_f32 v[140:141], v[140:141], 1.0 op_sel_hi:[1,0]
	v_pk_mul_f32 v[196:197], v[196:197], v[126:127]
	v_pk_mul_f32 v[198:199], v[198:199], v[128:129]
	v_pk_mul_f32 v[196:197], v[196:197], v[138:139]
	v_pk_mul_f32 v[198:199], v[198:199], v[140:141]
	v_cvt_pk_f16_f32 v196, v196, v197
	v_cvt_pk_f16_f32 v197, v198, v199
	v_add_u32_e32 v115, 0, v102
	v_lshlrev_b32_e32 v0, 12, v115
	v_add_u32_e32 v0, v0, v101
	v_lshrrev_b32_e32 v0, 1, v0
	v_lshl_add_u64 v[116:117], s[8:9], 0, v[0:1]
	global_store_dwordx2 v[116:117], v[196:197], off offset:64
	v_mul_f32_e32 v184, v200, v200
	v_fmac_f32_e32 v184, v201, v201
	v_fmac_f32_e32 v184, v202, v202
	v_fmac_f32_e32 v184, v203, v203
	v_pk_add_f32 v[142:143], v[142:143], 1.0 op_sel_hi:[1,0]
	v_pk_add_f32 v[144:145], v[144:145], 1.0 op_sel_hi:[1,0]
	v_pk_mul_f32 v[200:201], v[200:201], v[126:127]
	v_pk_mul_f32 v[202:203], v[202:203], v[128:129]
	v_pk_mul_f32 v[200:201], v[200:201], v[142:143]
	v_pk_mul_f32 v[202:203], v[202:203], v[144:145]
	v_cvt_pk_f16_f32 v200, v200, v201
	v_cvt_pk_f16_f32 v201, v202, v203
	v_add_u32_e32 v115, 8, v102
	v_lshlrev_b32_e32 v0, 12, v115
	v_add_u32_e32 v0, v0, v101
	v_lshrrev_b32_e32 v0, 1, v0
	v_lshl_add_u64 v[116:117], s[8:9], 0, v[0:1]
	global_store_dwordx2 v[116:117], v[200:201], off offset:64
	v_mul_f32_e32 v188, v204, v204
	v_fmac_f32_e32 v188, v205, v205
	v_fmac_f32_e32 v188, v206, v206
	v_fmac_f32_e32 v188, v207, v207
	v_pk_add_f32 v[146:147], v[146:147], 1.0 op_sel_hi:[1,0]
	v_pk_add_f32 v[148:149], v[148:149], 1.0 op_sel_hi:[1,0]
	v_pk_mul_f32 v[204:205], v[204:205], v[126:127]
	v_pk_mul_f32 v[206:207], v[206:207], v[128:129]
	v_pk_mul_f32 v[204:205], v[204:205], v[146:147]
	v_pk_mul_f32 v[206:207], v[206:207], v[148:149]
	v_cvt_pk_f16_f32 v204, v204, v205
	v_cvt_pk_f16_f32 v205, v206, v207
	v_add_u32_e32 v115, 16, v102
	v_lshlrev_b32_e32 v0, 12, v115
	v_add_u32_e32 v0, v0, v101
	v_lshrrev_b32_e32 v0, 1, v0
	v_lshl_add_u64 v[116:117], s[8:9], 0, v[0:1]
	global_store_dwordx2 v[116:117], v[204:205], off offset:64
	v_mul_f32_e32 v192, v208, v208
	v_fmac_f32_e32 v192, v209, v209
	v_fmac_f32_e32 v192, v210, v210
	v_fmac_f32_e32 v192, v211, v211
	v_pk_add_f32 v[118:119], v[118:119], 1.0 op_sel_hi:[1,0]
	v_pk_add_f32 v[120:121], v[120:121], 1.0 op_sel_hi:[1,0]
	v_pk_mul_f32 v[208:209], v[208:209], v[126:127]
	v_pk_mul_f32 v[210:211], v[210:211], v[128:129]
	v_pk_mul_f32 v[208:209], v[208:209], v[118:119]
	v_pk_mul_f32 v[210:211], v[210:211], v[120:121]
	v_cvt_pk_f16_f32 v208, v208, v209
	v_cvt_pk_f16_f32 v209, v210, v211
	v_add_u32_e32 v115, 24, v102
	v_lshlrev_b32_e32 v0, 12, v115
	v_add_u32_e32 v0, v0, v101
	v_lshrrev_b32_e32 v0, 1, v0
	v_lshl_add_u64 v[116:117], s[8:9], 0, v[0:1]
	global_store_dwordx2 v[116:117], v[208:209], off offset:64
	s_nop 1
	v_add_f32_dpp v180, v180, v180 quad_perm:[1,0,3,2] row_mask:0xf bank_mask:0xf bound_ctrl:1
	v_add_f32_dpp v184, v184, v184 quad_perm:[1,0,3,2] row_mask:0xf bank_mask:0xf bound_ctrl:1
	v_add_f32_dpp v188, v188, v188 quad_perm:[1,0,3,2] row_mask:0xf bank_mask:0xf bound_ctrl:1
	v_add_f32_dpp v192, v192, v192 quad_perm:[1,0,3,2] row_mask:0xf bank_mask:0xf bound_ctrl:1
	s_nop 1
	v_add_f32_dpp v180, v180, v180 quad_perm:[2,3,0,1] row_mask:0xf bank_mask:0xf bound_ctrl:1
	v_add_f32_dpp v184, v184, v184 quad_perm:[2,3,0,1] row_mask:0xf bank_mask:0xf bound_ctrl:1
	v_add_f32_dpp v188, v188, v188 quad_perm:[2,3,0,1] row_mask:0xf bank_mask:0xf bound_ctrl:1
	v_add_f32_dpp v192, v192, v192 quad_perm:[2,3,0,1] row_mask:0xf bank_mask:0xf bound_ctrl:1
	s_nop 1
	v_add_f32_dpp v180, v180, v180 row_half_mirror row_mask:0xf bank_mask:0xf bound_ctrl:1
	v_add_f32_dpp v184, v184, v184 row_half_mirror row_mask:0xf bank_mask:0xf bound_ctrl:1
	v_add_f32_dpp v188, v188, v188 row_half_mirror row_mask:0xf bank_mask:0xf bound_ctrl:1
	v_add_f32_dpp v192, v192, v192 row_half_mirror row_mask:0xf bank_mask:0xf bound_ctrl:1
	s_mov_b64 s[42:43], exec
	s_mov_b32 s20, 0x01010101
	s_mov_b32 exec_lo, s20
	s_mov_b32 exec_hi, s20
	v_add_u32_e32 v0, 0, v102
	v_lshlrev_b32_e32 v0, 2, v0
	v_lshl_add_u64 v[116:117], s[12:13], 0, v[0:1]
	global_atomic_add_f32 v[116:117], v180, off
	v_add_u32_e32 v0, 8, v102
	v_lshlrev_b32_e32 v0, 2, v0
	v_lshl_add_u64 v[116:117], s[12:13], 0, v[0:1]
	global_atomic_add_f32 v[116:117], v184, off
	v_add_u32_e32 v0, 16, v102
	v_lshlrev_b32_e32 v0, 2, v0
	v_lshl_add_u64 v[116:117], s[12:13], 0, v[0:1]
	global_atomic_add_f32 v[116:117], v188, off
	v_add_u32_e32 v0, 24, v102
	v_lshlrev_b32_e32 v0, 2, v0
	v_lshl_add_u64 v[116:117], s[12:13], 0, v[0:1]
	global_atomic_add_f32 v[116:117], v192, off
	s_mov_b64 exec, s[42:43]
.Lrt_a_x_0_1:
	ds_write_b128 v98, v[50:53] offset:0
	ds_write_b128 v98, v[54:57] offset:32
	ds_write_b128 v98, v[58:61] offset:64
	ds_write_b128 v98, v[62:65] offset:96
	ds_read_b128 v[180:183], v99 offset:0
	ds_read_b128 v[184:187], v99 offset:1152
	ds_read_b128 v[188:191], v99 offset:2304
	ds_read_b128 v[192:195], v99 offset:3456
	v_add_u32_e32 v115, 32, v102
	v_subrev_co_u32_e32 v103, vcc, 0x1000, v115
	v_lshrrev_b32_e32 v103, 11, v103
	v_add_u32_e32 v103, 1, v103
	s_nop 0
	v_cndmask_b32_e64 v103, v103, 0, vcc
	v_add_u32_e32 v0, s48, v103
	v_mul_u32_u24_e32 v0, 0x6000, v0
	v_add_u32_e32 v0, v0, v101
	v_lshl_add_u64 v[116:117], s[50:51], 0, v[0:1]
	global_load_dwordx4 v[212:215], v[116:117], off offset:0
	v_lshlrev_b32_e32 v0, 12, v115
	v_add_u32_e32 v0, v0, v101
	v_lshl_add_u64 v[104:105], s[6:7], 0, v[0:1]
	global_load_dwordx4 v[196:199], v[104:105], off offset:0
	s_and_b64 vcc, exec, s[54:55]
	s_cbranch_vccz .Lrt_a_a_1_0_0
	v_add_u32_e32 v0, s52, v103
	v_mul_u32_u24_e32 v0, 0x6000, v0
	v_add_u32_e32 v0, v0, v101
	v_lshl_add_u64 v[116:117], s[46:47], 0, v[0:1]
	global_load_dwordx4 v[138:141], v[116:117], off offset:0
.Lrt_a_a_1_0_0:
	v_add_u32_e32 v115, 40, v102
	v_subrev_co_u32_e32 v103, vcc, 0x1000, v115
	v_lshrrev_b32_e32 v103, 11, v103
	v_add_u32_e32 v103, 1, v103
	s_nop 0
	v_cndmask_b32_e64 v103, v103, 0, vcc
	v_add_u32_e32 v0, s48, v103
	v_mul_u32_u24_e32 v0, 0x6000, v0
	v_add_u32_e32 v0, v0, v101
	v_lshl_add_u64 v[116:117], s[50:51], 0, v[0:1]
	global_load_dwordx4 v[216:219], v[116:117], off offset:0
	v_lshlrev_b32_e32 v0, 12, v115
	v_add_u32_e32 v0, v0, v101
	v_lshl_add_u64 v[106:107], s[6:7], 0, v[0:1]
	global_load_dwordx4 v[200:203], v[106:107], off offset:0
	s_and_b64 vcc, exec, s[54:55]
	s_cbranch_vccz .Lrt_a_a_1_0_1
	v_add_u32_e32 v0, s52, v103
	v_mul_u32_u24_e32 v0, 0x6000, v0
	v_add_u32_e32 v0, v0, v101
	v_lshl_add_u64 v[116:117], s[46:47], 0, v[0:1]
	global_load_dwordx4 v[142:145], v[116:117], off offset:0
.Lrt_a_a_1_0_1:
	v_add_u32_e32 v115, 48, v102
	v_subrev_co_u32_e32 v103, vcc, 0x1000, v115
	v_lshrrev_b32_e32 v103, 11, v103
	v_add_u32_e32 v103, 1, v103
	s_nop 0
	v_cndmask_b32_e64 v103, v103, 0, vcc
	v_add_u32_e32 v0, s48, v103
	v_mul_u32_u24_e32 v0, 0x6000, v0
	v_add_u32_e32 v0, v0, v101
	v_lshl_add_u64 v[116:117], s[50:51], 0, v[0:1]
	global_load_dwordx4 v[220:223], v[116:117], off offset:0
	v_lshlrev_b32_e32 v0, 12, v115
	v_add_u32_e32 v0, v0, v101
	v_lshl_add_u64 v[108:109], s[6:7], 0, v[0:1]
	global_load_dwordx4 v[204:207], v[108:109], off offset:0
	s_and_b64 vcc, exec, s[54:55]
	s_cbranch_vccz .Lrt_a_a_1_0_2
	v_add_u32_e32 v0, s52, v103
	v_mul_u32_u24_e32 v0, 0x6000, v0
	v_add_u32_e32 v0, v0, v101
	v_lshl_add_u64 v[116:117], s[46:47], 0, v[0:1]
	global_load_dwordx4 v[146:149], v[116:117], off offset:0
.Lrt_a_a_1_0_2:
	v_add_u32_e32 v115, 56, v102
	v_subrev_co_u32_e32 v103, vcc, 0x1000, v115
	v_lshrrev_b32_e32 v103, 11, v103
	v_add_u32_e32 v103, 1, v103
	s_nop 0
	v_cndmask_b32_e64 v103, v103, 0, vcc
	v_add_u32_e32 v0, s48, v103
	v_mul_u32_u24_e32 v0, 0x6000, v0
	v_add_u32_e32 v0, v0, v101
	v_lshl_add_u64 v[116:117], s[50:51], 0, v[0:1]
	global_load_dwordx4 v[134:137], v[116:117], off offset:0
	v_lshlrev_b32_e32 v0, 12, v115
	v_add_u32_e32 v0, v0, v101
	v_lshl_add_u64 v[110:111], s[6:7], 0, v[0:1]
	global_load_dwordx4 v[208:211], v[110:111], off offset:0
	s_and_b64 vcc, exec, s[54:55]
	s_cbranch_vccz .Lrt_a_a_1_0_3
	v_add_u32_e32 v0, s52, v103
	v_mul_u32_u24_e32 v0, 0x6000, v0
	v_add_u32_e32 v0, v0, v101
	v_lshl_add_u64 v[116:117], s[46:47], 0, v[0:1]
	global_load_dwordx4 v[118:121], v[116:117], off offset:0
.Lrt_a_a_1_0_3:
	s_waitcnt vmcnt(0) lgkmcnt(0)
	v_pk_fma_f32 v[196:197], v[180:181], v[212:213], v[196:197]
	v_pk_fma_f32 v[198:199], v[182:183], v[214:215], v[198:199]
	v_pk_fma_f32 v[200:201], v[184:185], v[216:217], v[200:201]
	v_pk_fma_f32 v[202:203], v[186:187], v[218:219], v[202:203]
	v_pk_fma_f32 v[204:205], v[188:189], v[220:221], v[204:205]
	v_pk_fma_f32 v[206:207], v[190:191], v[222:223], v[206:207]
	v_pk_fma_f32 v[208:209], v[192:193], v[134:135], v[208:209]
	v_pk_fma_f32 v[210:211], v[194:195], v[136:137], v[210:211]
	global_store_dwordx4 v[104:105], v[196:199], off offset:0
	global_store_dwordx4 v[106:107], v[200:203], off offset:0
	global_store_dwordx4 v[108:109], v[204:207], off offset:0
	global_store_dwordx4 v[110:111], v[208:211], off offset:0
	s_and_b64 vcc, exec, s[54:55]
	s_cbranch_vccz .Lrt_a_x_1_0
	v_mul_f32_e32 v180, v196, v196
	v_fmac_f32_e32 v180, v197, v197
	v_fmac_f32_e32 v180, v198, v198
	v_fmac_f32_e32 v180, v199, v199
	v_pk_add_f32 v[138:139], v[138:139], 1.0 op_sel_hi:[1,0]
	v_pk_add_f32 v[140:141], v[140:141], 1.0 op_sel_hi:[1,0]
	v_pk_mul_f32 v[196:197], v[196:197], v[122:123]
	v_pk_mul_f32 v[198:199], v[198:199], v[124:125]
	v_pk_mul_f32 v[196:197], v[196:197], v[138:139]
	v_pk_mul_f32 v[198:199], v[198:199], v[140:141]
	v_cvt_pk_f16_f32 v196, v196, v197
	v_cvt_pk_f16_f32 v197, v198, v199
	v_add_u32_e32 v115, 32, v102
	v_lshlrev_b32_e32 v0, 12, v115
	v_add_u32_e32 v0, v0, v101
	v_lshrrev_b32_e32 v0, 1, v0
	v_lshl_add_u64 v[116:117], s[8:9], 0, v[0:1]
	global_store_dwordx2 v[116:117], v[196:197], off offset:0
	v_mul_f32_e32 v184, v200, v200
	v_fmac_f32_e32 v184, v201, v201
	v_fmac_f32_e32 v184, v202, v202
	v_fmac_f32_e32 v184, v203, v203
	v_pk_add_f32 v[142:143], v[142:143], 1.0 op_sel_hi:[1,0]
	v_pk_add_f32 v[144:145], v[144:145], 1.0 op_sel_hi:[1,0]
	v_pk_mul_f32 v[200:201], v[200:201], v[122:123]
	v_pk_mul_f32 v[202:203], v[202:203], v[124:125]
	v_pk_mul_f32 v[200:201], v[200:201], v[142:143]
	v_pk_mul_f32 v[202:203], v[202:203], v[144:145]
	v_cvt_pk_f16_f32 v200, v200, v201
	v_cvt_pk_f16_f32 v201, v202, v203
	v_add_u32_e32 v115, 40, v102
	v_lshlrev_b32_e32 v0, 12, v115
	v_add_u32_e32 v0, v0, v101
	v_lshrrev_b32_e32 v0, 1, v0
	v_lshl_add_u64 v[116:117], s[8:9], 0, v[0:1]
	global_store_dwordx2 v[116:117], v[200:201], off offset:0
	v_mul_f32_e32 v188, v204, v204
	v_fmac_f32_e32 v188, v205, v205
	v_fmac_f32_e32 v188, v206, v206
	v_fmac_f32_e32 v188, v207, v207
	v_pk_add_f32 v[146:147], v[146:147], 1.0 op_sel_hi:[1,0]
	v_pk_add_f32 v[148:149], v[148:149], 1.0 op_sel_hi:[1,0]
	v_pk_mul_f32 v[204:205], v[204:205], v[122:123]
	v_pk_mul_f32 v[206:207], v[206:207], v[124:125]
	v_pk_mul_f32 v[204:205], v[204:205], v[146:147]
	v_pk_mul_f32 v[206:207], v[206:207], v[148:149]
	v_cvt_pk_f16_f32 v204, v204, v205
	v_cvt_pk_f16_f32 v205, v206, v207
	v_add_u32_e32 v115, 48, v102
	v_lshlrev_b32_e32 v0, 12, v115
	v_add_u32_e32 v0, v0, v101
	v_lshrrev_b32_e32 v0, 1, v0
	v_lshl_add_u64 v[116:117], s[8:9], 0, v[0:1]
	global_store_dwordx2 v[116:117], v[204:205], off offset:0
	v_mul_f32_e32 v192, v208, v208
	v_fmac_f32_e32 v192, v209, v209
	v_fmac_f32_e32 v192, v210, v210
	v_fmac_f32_e32 v192, v211, v211
	v_pk_add_f32 v[118:119], v[118:119], 1.0 op_sel_hi:[1,0]
	v_pk_add_f32 v[120:121], v[120:121], 1.0 op_sel_hi:[1,0]
	v_pk_mul_f32 v[208:209], v[208:209], v[122:123]
	v_pk_mul_f32 v[210:211], v[210:211], v[124:125]
	v_pk_mul_f32 v[208:209], v[208:209], v[118:119]
	v_pk_mul_f32 v[210:211], v[210:211], v[120:121]
	v_cvt_pk_f16_f32 v208, v208, v209
	v_cvt_pk_f16_f32 v209, v210, v211
	v_add_u32_e32 v115, 56, v102
	v_lshlrev_b32_e32 v0, 12, v115
	v_add_u32_e32 v0, v0, v101
	v_lshrrev_b32_e32 v0, 1, v0
	v_lshl_add_u64 v[116:117], s[8:9], 0, v[0:1]
	global_store_dwordx2 v[116:117], v[208:209], off offset:0
	s_nop 1
	v_add_f32_dpp v180, v180, v180 quad_perm:[1,0,3,2] row_mask:0xf bank_mask:0xf bound_ctrl:1
	v_add_f32_dpp v184, v184, v184 quad_perm:[1,0,3,2] row_mask:0xf bank_mask:0xf bound_ctrl:1
	v_add_f32_dpp v188, v188, v188 quad_perm:[1,0,3,2] row_mask:0xf bank_mask:0xf bound_ctrl:1
	v_add_f32_dpp v192, v192, v192 quad_perm:[1,0,3,2] row_mask:0xf bank_mask:0xf bound_ctrl:1
	s_nop 1
	v_add_f32_dpp v180, v180, v180 quad_perm:[2,3,0,1] row_mask:0xf bank_mask:0xf bound_ctrl:1
	v_add_f32_dpp v184, v184, v184 quad_perm:[2,3,0,1] row_mask:0xf bank_mask:0xf bound_ctrl:1
	v_add_f32_dpp v188, v188, v188 quad_perm:[2,3,0,1] row_mask:0xf bank_mask:0xf bound_ctrl:1
	v_add_f32_dpp v192, v192, v192 quad_perm:[2,3,0,1] row_mask:0xf bank_mask:0xf bound_ctrl:1
	s_nop 1
	v_add_f32_dpp v180, v180, v180 row_half_mirror row_mask:0xf bank_mask:0xf bound_ctrl:1
	v_add_f32_dpp v184, v184, v184 row_half_mirror row_mask:0xf bank_mask:0xf bound_ctrl:1
	v_add_f32_dpp v188, v188, v188 row_half_mirror row_mask:0xf bank_mask:0xf bound_ctrl:1
	v_add_f32_dpp v192, v192, v192 row_half_mirror row_mask:0xf bank_mask:0xf bound_ctrl:1
	s_mov_b64 s[42:43], exec
	s_mov_b32 s20, 0x01010101
	s_mov_b32 exec_lo, s20
	s_mov_b32 exec_hi, s20
	v_add_u32_e32 v0, 32, v102
	v_lshlrev_b32_e32 v0, 2, v0
	v_lshl_add_u64 v[116:117], s[12:13], 0, v[0:1]
	global_atomic_add_f32 v[116:117], v180, off
	v_add_u32_e32 v0, 40, v102
	v_lshlrev_b32_e32 v0, 2, v0
	v_lshl_add_u64 v[116:117], s[12:13], 0, v[0:1]
	global_atomic_add_f32 v[116:117], v184, off
	v_add_u32_e32 v0, 48, v102
	v_lshlrev_b32_e32 v0, 2, v0
	v_lshl_add_u64 v[116:117], s[12:13], 0, v[0:1]
	global_atomic_add_f32 v[116:117], v188, off
	v_add_u32_e32 v0, 56, v102
	v_lshlrev_b32_e32 v0, 2, v0
	v_lshl_add_u64 v[116:117], s[12:13], 0, v[0:1]
	global_atomic_add_f32 v[116:117], v192, off
	s_mov_b64 exec, s[42:43]
.Lrt_a_x_1_0:
	ds_write_b128 v98, v[34:37] offset:4608
	ds_write_b128 v98, v[38:41] offset:4640
	ds_write_b128 v98, v[42:45] offset:4672
	ds_write_b128 v98, v[46:49] offset:4704
	ds_read_b128 v[180:183], v99 offset:4608
	ds_read_b128 v[184:187], v99 offset:5760
	ds_read_b128 v[188:191], v99 offset:6912
	ds_read_b128 v[192:195], v99 offset:8064
	v_add_u32_e32 v115, 32, v102
	v_subrev_co_u32_e32 v103, vcc, 0x1000, v115
	v_lshrrev_b32_e32 v103, 11, v103
	v_add_u32_e32 v103, 1, v103
	s_nop 0
	v_cndmask_b32_e64 v103, v103, 0, vcc
	v_add_u32_e32 v0, s48, v103
	v_mul_u32_u24_e32 v0, 0x6000, v0
	v_add_u32_e32 v0, v0, v101
	v_lshl_add_u64 v[116:117], s[50:51], 0, v[0:1]
	global_load_dwordx4 v[212:215], v[116:117], off offset:128
	v_lshlrev_b32_e32 v0, 12, v115
	v_add_u32_e32 v0, v0, v101
	v_lshl_add_u64 v[104:105], s[6:7], 0, v[0:1]
	global_load_dwordx4 v[196:199], v[104:105], off offset:128
	s_and_b64 vcc, exec, s[54:55]
	s_cbranch_vccz .Lrt_a_a_1_1_0
	v_add_u32_e32 v0, s52, v103
	v_mul_u32_u24_e32 v0, 0x6000, v0
	v_add_u32_e32 v0, v0, v101
	v_lshl_add_u64 v[116:117], s[46:47], 0, v[0:1]
	global_load_dwordx4 v[138:141], v[116:117], off offset:128
.Lrt_a_a_1_1_0:
	v_add_u32_e32 v115, 40, v102
	v_subrev_co_u32_e32 v103, vcc, 0x1000, v115
	v_lshrrev_b32_e32 v103, 11, v103
	v_add_u32_e32 v103, 1, v103
	s_nop 0
	v_cndmask_b32_e64 v103, v103, 0, vcc
	v_add_u32_e32 v0, s48, v103
	v_mul_u32_u24_e32 v0, 0x6000, v0
	v_add_u32_e32 v0, v0, v101
	v_lshl_add_u64 v[116:117], s[50:51], 0, v[0:1]
	global_load_dwordx4 v[216:219], v[116:117], off offset:128
	v_lshlrev_b32_e32 v0, 12, v115
	v_add_u32_e32 v0, v0, v101
	v_lshl_add_u64 v[106:107], s[6:7], 0, v[0:1]
	global_load_dwordx4 v[200:203], v[106:107], off offset:128
	s_and_b64 vcc, exec, s[54:55]
	s_cbranch_vccz .Lrt_a_a_1_1_1
	v_add_u32_e32 v0, s52, v103
	v_mul_u32_u24_e32 v0, 0x6000, v0
	v_add_u32_e32 v0, v0, v101
	v_lshl_add_u64 v[116:117], s[46:47], 0, v[0:1]
	global_load_dwordx4 v[142:145], v[116:117], off offset:128
.Lrt_a_a_1_1_1:
	v_add_u32_e32 v115, 48, v102
	v_subrev_co_u32_e32 v103, vcc, 0x1000, v115
	v_lshrrev_b32_e32 v103, 11, v103
	v_add_u32_e32 v103, 1, v103
	s_nop 0
	v_cndmask_b32_e64 v103, v103, 0, vcc
	v_add_u32_e32 v0, s48, v103
	v_mul_u32_u24_e32 v0, 0x6000, v0
	v_add_u32_e32 v0, v0, v101
	v_lshl_add_u64 v[116:117], s[50:51], 0, v[0:1]
	global_load_dwordx4 v[220:223], v[116:117], off offset:128
	v_lshlrev_b32_e32 v0, 12, v115
	v_add_u32_e32 v0, v0, v101
	v_lshl_add_u64 v[108:109], s[6:7], 0, v[0:1]
	global_load_dwordx4 v[204:207], v[108:109], off offset:128
	s_and_b64 vcc, exec, s[54:55]
	s_cbranch_vccz .Lrt_a_a_1_1_2
	v_add_u32_e32 v0, s52, v103
	v_mul_u32_u24_e32 v0, 0x6000, v0
	v_add_u32_e32 v0, v0, v101
	v_lshl_add_u64 v[116:117], s[46:47], 0, v[0:1]
	global_load_dwordx4 v[146:149], v[116:117], off offset:128
.Lrt_a_a_1_1_2:
	v_add_u32_e32 v115, 56, v102
	v_subrev_co_u32_e32 v103, vcc, 0x1000, v115
	v_lshrrev_b32_e32 v103, 11, v103
	v_add_u32_e32 v103, 1, v103
	s_nop 0
	v_cndmask_b32_e64 v103, v103, 0, vcc
	v_add_u32_e32 v0, s48, v103
	v_mul_u32_u24_e32 v0, 0x6000, v0
	v_add_u32_e32 v0, v0, v101
	v_lshl_add_u64 v[116:117], s[50:51], 0, v[0:1]
	global_load_dwordx4 v[134:137], v[116:117], off offset:128
	v_lshlrev_b32_e32 v0, 12, v115
	v_add_u32_e32 v0, v0, v101
	v_lshl_add_u64 v[110:111], s[6:7], 0, v[0:1]
	global_load_dwordx4 v[208:211], v[110:111], off offset:128
	s_and_b64 vcc, exec, s[54:55]
	s_cbranch_vccz .Lrt_a_a_1_1_3
	v_add_u32_e32 v0, s52, v103
	v_mul_u32_u24_e32 v0, 0x6000, v0
	v_add_u32_e32 v0, v0, v101
	v_lshl_add_u64 v[116:117], s[46:47], 0, v[0:1]
	global_load_dwordx4 v[118:121], v[116:117], off offset:128
.Lrt_a_a_1_1_3:
	s_waitcnt vmcnt(0) lgkmcnt(0)
	v_pk_fma_f32 v[196:197], v[180:181], v[212:213], v[196:197]
	v_pk_fma_f32 v[198:199], v[182:183], v[214:215], v[198:199]
	v_pk_fma_f32 v[200:201], v[184:185], v[216:217], v[200:201]
	v_pk_fma_f32 v[202:203], v[186:187], v[218:219], v[202:203]
	v_pk_fma_f32 v[204:205], v[188:189], v[220:221], v[204:205]
	v_pk_fma_f32 v[206:207], v[190:191], v[222:223], v[206:207]
	v_pk_fma_f32 v[208:209], v[192:193], v[134:135], v[208:209]
	v_pk_fma_f32 v[210:211], v[194:195], v[136:137], v[210:211]
	global_store_dwordx4 v[104:105], v[196:199], off offset:128
	global_store_dwordx4 v[106:107], v[200:203], off offset:128
	global_store_dwordx4 v[108:109], v[204:207], off offset:128
	global_store_dwordx4 v[110:111], v[208:211], off offset:128
	s_and_b64 vcc, exec, s[54:55]
	s_cbranch_vccz .Lrt_a_x_1_1
	v_mul_f32_e32 v180, v196, v196
	v_fmac_f32_e32 v180, v197, v197
	v_fmac_f32_e32 v180, v198, v198
	v_fmac_f32_e32 v180, v199, v199
	v_pk_add_f32 v[138:139], v[138:139], 1.0 op_sel_hi:[1,0]
	v_pk_add_f32 v[140:141], v[140:141], 1.0 op_sel_hi:[1,0]
	v_pk_mul_f32 v[196:197], v[196:197], v[126:127]
	v_pk_mul_f32 v[198:199], v[198:199], v[128:129]
	v_pk_mul_f32 v[196:197], v[196:197], v[138:139]
	v_pk_mul_f32 v[198:199], v[198:199], v[140:141]
	v_cvt_pk_f16_f32 v196, v196, v197
	v_cvt_pk_f16_f32 v197, v198, v199
	v_add_u32_e32 v115, 32, v102
	v_lshlrev_b32_e32 v0, 12, v115
	v_add_u32_e32 v0, v0, v101
	v_lshrrev_b32_e32 v0, 1, v0
	v_lshl_add_u64 v[116:117], s[8:9], 0, v[0:1]
	global_store_dwordx2 v[116:117], v[196:197], off offset:64
	v_mul_f32_e32 v184, v200, v200
	v_fmac_f32_e32 v184, v201, v201
	v_fmac_f32_e32 v184, v202, v202
	v_fmac_f32_e32 v184, v203, v203
	v_pk_add_f32 v[142:143], v[142:143], 1.0 op_sel_hi:[1,0]
	v_pk_add_f32 v[144:145], v[144:145], 1.0 op_sel_hi:[1,0]
	v_pk_mul_f32 v[200:201], v[200:201], v[126:127]
	v_pk_mul_f32 v[202:203], v[202:203], v[128:129]
	v_pk_mul_f32 v[200:201], v[200:201], v[142:143]
	v_pk_mul_f32 v[202:203], v[202:203], v[144:145]
	v_cvt_pk_f16_f32 v200, v200, v201
	v_cvt_pk_f16_f32 v201, v202, v203
	v_add_u32_e32 v115, 40, v102
	v_lshlrev_b32_e32 v0, 12, v115
	v_add_u32_e32 v0, v0, v101
	v_lshrrev_b32_e32 v0, 1, v0
	v_lshl_add_u64 v[116:117], s[8:9], 0, v[0:1]
	global_store_dwordx2 v[116:117], v[200:201], off offset:64
	v_mul_f32_e32 v188, v204, v204
	v_fmac_f32_e32 v188, v205, v205
	v_fmac_f32_e32 v188, v206, v206
	v_fmac_f32_e32 v188, v207, v207
	v_pk_add_f32 v[146:147], v[146:147], 1.0 op_sel_hi:[1,0]
	v_pk_add_f32 v[148:149], v[148:149], 1.0 op_sel_hi:[1,0]
	v_pk_mul_f32 v[204:205], v[204:205], v[126:127]
	v_pk_mul_f32 v[206:207], v[206:207], v[128:129]
	v_pk_mul_f32 v[204:205], v[204:205], v[146:147]
	v_pk_mul_f32 v[206:207], v[206:207], v[148:149]
	v_cvt_pk_f16_f32 v204, v204, v205
	v_cvt_pk_f16_f32 v205, v206, v207
	v_add_u32_e32 v115, 48, v102
	v_lshlrev_b32_e32 v0, 12, v115
	v_add_u32_e32 v0, v0, v101
	v_lshrrev_b32_e32 v0, 1, v0
	v_lshl_add_u64 v[116:117], s[8:9], 0, v[0:1]
	global_store_dwordx2 v[116:117], v[204:205], off offset:64
	v_mul_f32_e32 v192, v208, v208
	v_fmac_f32_e32 v192, v209, v209
	v_fmac_f32_e32 v192, v210, v210
	v_fmac_f32_e32 v192, v211, v211
	v_pk_add_f32 v[118:119], v[118:119], 1.0 op_sel_hi:[1,0]
	v_pk_add_f32 v[120:121], v[120:121], 1.0 op_sel_hi:[1,0]
	v_pk_mul_f32 v[208:209], v[208:209], v[126:127]
	v_pk_mul_f32 v[210:211], v[210:211], v[128:129]
	v_pk_mul_f32 v[208:209], v[208:209], v[118:119]
	v_pk_mul_f32 v[210:211], v[210:211], v[120:121]
	v_cvt_pk_f16_f32 v208, v208, v209
	v_cvt_pk_f16_f32 v209, v210, v211
	v_add_u32_e32 v115, 56, v102
	v_lshlrev_b32_e32 v0, 12, v115
	v_add_u32_e32 v0, v0, v101
	v_lshrrev_b32_e32 v0, 1, v0
	v_lshl_add_u64 v[116:117], s[8:9], 0, v[0:1]
	global_store_dwordx2 v[116:117], v[208:209], off offset:64
	s_nop 1
	v_add_f32_dpp v180, v180, v180 quad_perm:[1,0,3,2] row_mask:0xf bank_mask:0xf bound_ctrl:1
	v_add_f32_dpp v184, v184, v184 quad_perm:[1,0,3,2] row_mask:0xf bank_mask:0xf bound_ctrl:1
	v_add_f32_dpp v188, v188, v188 quad_perm:[1,0,3,2] row_mask:0xf bank_mask:0xf bound_ctrl:1
	v_add_f32_dpp v192, v192, v192 quad_perm:[1,0,3,2] row_mask:0xf bank_mask:0xf bound_ctrl:1
	s_nop 1
	v_add_f32_dpp v180, v180, v180 quad_perm:[2,3,0,1] row_mask:0xf bank_mask:0xf bound_ctrl:1
	v_add_f32_dpp v184, v184, v184 quad_perm:[2,3,0,1] row_mask:0xf bank_mask:0xf bound_ctrl:1
	v_add_f32_dpp v188, v188, v188 quad_perm:[2,3,0,1] row_mask:0xf bank_mask:0xf bound_ctrl:1
	v_add_f32_dpp v192, v192, v192 quad_perm:[2,3,0,1] row_mask:0xf bank_mask:0xf bound_ctrl:1
	s_nop 1
	v_add_f32_dpp v180, v180, v180 row_half_mirror row_mask:0xf bank_mask:0xf bound_ctrl:1
	v_add_f32_dpp v184, v184, v184 row_half_mirror row_mask:0xf bank_mask:0xf bound_ctrl:1
	v_add_f32_dpp v188, v188, v188 row_half_mirror row_mask:0xf bank_mask:0xf bound_ctrl:1
	v_add_f32_dpp v192, v192, v192 row_half_mirror row_mask:0xf bank_mask:0xf bound_ctrl:1
	s_mov_b64 s[42:43], exec
	s_mov_b32 s20, 0x01010101
	s_mov_b32 exec_lo, s20
	s_mov_b32 exec_hi, s20
	v_add_u32_e32 v0, 32, v102
	v_lshlrev_b32_e32 v0, 2, v0
	v_lshl_add_u64 v[116:117], s[12:13], 0, v[0:1]
	global_atomic_add_f32 v[116:117], v180, off
	v_add_u32_e32 v0, 40, v102
	v_lshlrev_b32_e32 v0, 2, v0
	v_lshl_add_u64 v[116:117], s[12:13], 0, v[0:1]
	global_atomic_add_f32 v[116:117], v184, off
	v_add_u32_e32 v0, 48, v102
	v_lshlrev_b32_e32 v0, 2, v0
	v_lshl_add_u64 v[116:117], s[12:13], 0, v[0:1]
	global_atomic_add_f32 v[116:117], v188, off
	v_add_u32_e32 v0, 56, v102
	v_lshlrev_b32_e32 v0, 2, v0
	v_lshl_add_u64 v[116:117], s[12:13], 0, v[0:1]
	global_atomic_add_f32 v[116:117], v192, off
	s_mov_b64 exec, s[42:43]
.Lrt_a_x_1_1:
	ds_write_b128 v98, v[18:21] offset:0
	ds_write_b128 v98, v[22:25] offset:32
	ds_write_b128 v98, v[26:29] offset:64
	ds_write_b128 v98, v[30:33] offset:96
	ds_read_b128 v[180:183], v99 offset:0
	ds_read_b128 v[184:187], v99 offset:1152
	ds_read_b128 v[188:191], v99 offset:2304
	ds_read_b128 v[192:195], v99 offset:3456
	v_add_u32_e32 v115, 64, v102
	v_subrev_co_u32_e32 v103, vcc, 0x1000, v115
	v_lshrrev_b32_e32 v103, 11, v103
	v_add_u32_e32 v103, 1, v103
	s_nop 0
	v_cndmask_b32_e64 v103, v103, 0, vcc
	v_add_u32_e32 v0, s48, v103
	v_mul_u32_u24_e32 v0, 0x6000, v0
	v_add_u32_e32 v0, v0, v101
	v_lshl_add_u64 v[116:117], s[50:51], 0, v[0:1]
	global_load_dwordx4 v[212:215], v[116:117], off offset:0
	v_lshlrev_b32_e32 v0, 12, v115
	v_add_u32_e32 v0, v0, v101
	v_lshl_add_u64 v[104:105], s[6:7], 0, v[0:1]
	global_load_dwordx4 v[196:199], v[104:105], off offset:0
	s_and_b64 vcc, exec, s[54:55]
	s_cbranch_vccz .Lrt_a_a_2_0_0
	v_add_u32_e32 v0, s52, v103
	v_mul_u32_u24_e32 v0, 0x6000, v0
	v_add_u32_e32 v0, v0, v101
	v_lshl_add_u64 v[116:117], s[46:47], 0, v[0:1]
	global_load_dwordx4 v[138:141], v[116:117], off offset:0
.Lrt_a_a_2_0_0:
	v_add_u32_e32 v115, 72, v102
	v_subrev_co_u32_e32 v103, vcc, 0x1000, v115
	v_lshrrev_b32_e32 v103, 11, v103
	v_add_u32_e32 v103, 1, v103
	s_nop 0
	v_cndmask_b32_e64 v103, v103, 0, vcc
	v_add_u32_e32 v0, s48, v103
	v_mul_u32_u24_e32 v0, 0x6000, v0
	v_add_u32_e32 v0, v0, v101
	v_lshl_add_u64 v[116:117], s[50:51], 0, v[0:1]
	global_load_dwordx4 v[216:219], v[116:117], off offset:0
	v_lshlrev_b32_e32 v0, 12, v115
	v_add_u32_e32 v0, v0, v101
	v_lshl_add_u64 v[106:107], s[6:7], 0, v[0:1]
	global_load_dwordx4 v[200:203], v[106:107], off offset:0
	s_and_b64 vcc, exec, s[54:55]
	s_cbranch_vccz .Lrt_a_a_2_0_1
	v_add_u32_e32 v0, s52, v103
	v_mul_u32_u24_e32 v0, 0x6000, v0
	v_add_u32_e32 v0, v0, v101
	v_lshl_add_u64 v[116:117], s[46:47], 0, v[0:1]
	global_load_dwordx4 v[142:145], v[116:117], off offset:0
.Lrt_a_a_2_0_1:
	v_add_u32_e32 v115, 80, v102
	v_subrev_co_u32_e32 v103, vcc, 0x1000, v115
	v_lshrrev_b32_e32 v103, 11, v103
	v_add_u32_e32 v103, 1, v103
	s_nop 0
	v_cndmask_b32_e64 v103, v103, 0, vcc
	v_add_u32_e32 v0, s48, v103
	v_mul_u32_u24_e32 v0, 0x6000, v0
	v_add_u32_e32 v0, v0, v101
	v_lshl_add_u64 v[116:117], s[50:51], 0, v[0:1]
	global_load_dwordx4 v[220:223], v[116:117], off offset:0
	v_lshlrev_b32_e32 v0, 12, v115
	v_add_u32_e32 v0, v0, v101
	v_lshl_add_u64 v[108:109], s[6:7], 0, v[0:1]
	global_load_dwordx4 v[204:207], v[108:109], off offset:0
	s_and_b64 vcc, exec, s[54:55]
	s_cbranch_vccz .Lrt_a_a_2_0_2
	v_add_u32_e32 v0, s52, v103
	v_mul_u32_u24_e32 v0, 0x6000, v0
	v_add_u32_e32 v0, v0, v101
	v_lshl_add_u64 v[116:117], s[46:47], 0, v[0:1]
	global_load_dwordx4 v[146:149], v[116:117], off offset:0
.Lrt_a_a_2_0_2:
	v_add_u32_e32 v115, 88, v102
	v_subrev_co_u32_e32 v103, vcc, 0x1000, v115
	v_lshrrev_b32_e32 v103, 11, v103
	v_add_u32_e32 v103, 1, v103
	s_nop 0
	v_cndmask_b32_e64 v103, v103, 0, vcc
	v_add_u32_e32 v0, s48, v103
	v_mul_u32_u24_e32 v0, 0x6000, v0
	v_add_u32_e32 v0, v0, v101
	v_lshl_add_u64 v[116:117], s[50:51], 0, v[0:1]
	global_load_dwordx4 v[134:137], v[116:117], off offset:0
	v_lshlrev_b32_e32 v0, 12, v115
	v_add_u32_e32 v0, v0, v101
	v_lshl_add_u64 v[110:111], s[6:7], 0, v[0:1]
	global_load_dwordx4 v[208:211], v[110:111], off offset:0
	s_and_b64 vcc, exec, s[54:55]
	s_cbranch_vccz .Lrt_a_a_2_0_3
	v_add_u32_e32 v0, s52, v103
	v_mul_u32_u24_e32 v0, 0x6000, v0
	v_add_u32_e32 v0, v0, v101
	v_lshl_add_u64 v[116:117], s[46:47], 0, v[0:1]
	global_load_dwordx4 v[118:121], v[116:117], off offset:0
.Lrt_a_a_2_0_3:
	s_waitcnt vmcnt(0) lgkmcnt(0)
	v_pk_fma_f32 v[196:197], v[180:181], v[212:213], v[196:197]
	v_pk_fma_f32 v[198:199], v[182:183], v[214:215], v[198:199]
	v_pk_fma_f32 v[200:201], v[184:185], v[216:217], v[200:201]
	v_pk_fma_f32 v[202:203], v[186:187], v[218:219], v[202:203]
	v_pk_fma_f32 v[204:205], v[188:189], v[220:221], v[204:205]
	v_pk_fma_f32 v[206:207], v[190:191], v[222:223], v[206:207]
	v_pk_fma_f32 v[208:209], v[192:193], v[134:135], v[208:209]
	v_pk_fma_f32 v[210:211], v[194:195], v[136:137], v[210:211]
	global_store_dwordx4 v[104:105], v[196:199], off offset:0
	global_store_dwordx4 v[106:107], v[200:203], off offset:0
	global_store_dwordx4 v[108:109], v[204:207], off offset:0
	global_store_dwordx4 v[110:111], v[208:211], off offset:0
	s_and_b64 vcc, exec, s[54:55]
	s_cbranch_vccz .Lrt_a_x_2_0
	v_mul_f32_e32 v180, v196, v196
	v_fmac_f32_e32 v180, v197, v197
	v_fmac_f32_e32 v180, v198, v198
	v_fmac_f32_e32 v180, v199, v199
	v_pk_add_f32 v[138:139], v[138:139], 1.0 op_sel_hi:[1,0]
	v_pk_add_f32 v[140:141], v[140:141], 1.0 op_sel_hi:[1,0]
	v_pk_mul_f32 v[196:197], v[196:197], v[122:123]
	v_pk_mul_f32 v[198:199], v[198:199], v[124:125]
	v_pk_mul_f32 v[196:197], v[196:197], v[138:139]
	v_pk_mul_f32 v[198:199], v[198:199], v[140:141]
	v_cvt_pk_f16_f32 v196, v196, v197
	v_cvt_pk_f16_f32 v197, v198, v199
	v_add_u32_e32 v115, 64, v102
	v_lshlrev_b32_e32 v0, 12, v115
	v_add_u32_e32 v0, v0, v101
	v_lshrrev_b32_e32 v0, 1, v0
	v_lshl_add_u64 v[116:117], s[8:9], 0, v[0:1]
	global_store_dwordx2 v[116:117], v[196:197], off offset:0
	v_mul_f32_e32 v184, v200, v200
	v_fmac_f32_e32 v184, v201, v201
	v_fmac_f32_e32 v184, v202, v202
	v_fmac_f32_e32 v184, v203, v203
	v_pk_add_f32 v[142:143], v[142:143], 1.0 op_sel_hi:[1,0]
	v_pk_add_f32 v[144:145], v[144:145], 1.0 op_sel_hi:[1,0]
	v_pk_mul_f32 v[200:201], v[200:201], v[122:123]
	v_pk_mul_f32 v[202:203], v[202:203], v[124:125]
	v_pk_mul_f32 v[200:201], v[200:201], v[142:143]
	v_pk_mul_f32 v[202:203], v[202:203], v[144:145]
	v_cvt_pk_f16_f32 v200, v200, v201
	v_cvt_pk_f16_f32 v201, v202, v203
	v_add_u32_e32 v115, 72, v102
	v_lshlrev_b32_e32 v0, 12, v115
	v_add_u32_e32 v0, v0, v101
	v_lshrrev_b32_e32 v0, 1, v0
	v_lshl_add_u64 v[116:117], s[8:9], 0, v[0:1]
	global_store_dwordx2 v[116:117], v[200:201], off offset:0
	v_mul_f32_e32 v188, v204, v204
	v_fmac_f32_e32 v188, v205, v205
	v_fmac_f32_e32 v188, v206, v206
	v_fmac_f32_e32 v188, v207, v207
	v_pk_add_f32 v[146:147], v[146:147], 1.0 op_sel_hi:[1,0]
	v_pk_add_f32 v[148:149], v[148:149], 1.0 op_sel_hi:[1,0]
	v_pk_mul_f32 v[204:205], v[204:205], v[122:123]
	v_pk_mul_f32 v[206:207], v[206:207], v[124:125]
	v_pk_mul_f32 v[204:205], v[204:205], v[146:147]
	v_pk_mul_f32 v[206:207], v[206:207], v[148:149]
	v_cvt_pk_f16_f32 v204, v204, v205
	v_cvt_pk_f16_f32 v205, v206, v207
	v_add_u32_e32 v115, 80, v102
	v_lshlrev_b32_e32 v0, 12, v115
	v_add_u32_e32 v0, v0, v101
	v_lshrrev_b32_e32 v0, 1, v0
	v_lshl_add_u64 v[116:117], s[8:9], 0, v[0:1]
	global_store_dwordx2 v[116:117], v[204:205], off offset:0
	v_mul_f32_e32 v192, v208, v208
	v_fmac_f32_e32 v192, v209, v209
	v_fmac_f32_e32 v192, v210, v210
	v_fmac_f32_e32 v192, v211, v211
	v_pk_add_f32 v[118:119], v[118:119], 1.0 op_sel_hi:[1,0]
	v_pk_add_f32 v[120:121], v[120:121], 1.0 op_sel_hi:[1,0]
	v_pk_mul_f32 v[208:209], v[208:209], v[122:123]
	v_pk_mul_f32 v[210:211], v[210:211], v[124:125]
	v_pk_mul_f32 v[208:209], v[208:209], v[118:119]
	v_pk_mul_f32 v[210:211], v[210:211], v[120:121]
	v_cvt_pk_f16_f32 v208, v208, v209
	v_cvt_pk_f16_f32 v209, v210, v211
	v_add_u32_e32 v115, 88, v102
	v_lshlrev_b32_e32 v0, 12, v115
	v_add_u32_e32 v0, v0, v101
	v_lshrrev_b32_e32 v0, 1, v0
	v_lshl_add_u64 v[116:117], s[8:9], 0, v[0:1]
	global_store_dwordx2 v[116:117], v[208:209], off offset:0
	s_nop 1
	v_add_f32_dpp v180, v180, v180 quad_perm:[1,0,3,2] row_mask:0xf bank_mask:0xf bound_ctrl:1
	v_add_f32_dpp v184, v184, v184 quad_perm:[1,0,3,2] row_mask:0xf bank_mask:0xf bound_ctrl:1
	v_add_f32_dpp v188, v188, v188 quad_perm:[1,0,3,2] row_mask:0xf bank_mask:0xf bound_ctrl:1
	v_add_f32_dpp v192, v192, v192 quad_perm:[1,0,3,2] row_mask:0xf bank_mask:0xf bound_ctrl:1
	s_nop 1
	v_add_f32_dpp v180, v180, v180 quad_perm:[2,3,0,1] row_mask:0xf bank_mask:0xf bound_ctrl:1
	v_add_f32_dpp v184, v184, v184 quad_perm:[2,3,0,1] row_mask:0xf bank_mask:0xf bound_ctrl:1
	v_add_f32_dpp v188, v188, v188 quad_perm:[2,3,0,1] row_mask:0xf bank_mask:0xf bound_ctrl:1
	v_add_f32_dpp v192, v192, v192 quad_perm:[2,3,0,1] row_mask:0xf bank_mask:0xf bound_ctrl:1
	s_nop 1
	v_add_f32_dpp v180, v180, v180 row_half_mirror row_mask:0xf bank_mask:0xf bound_ctrl:1
	v_add_f32_dpp v184, v184, v184 row_half_mirror row_mask:0xf bank_mask:0xf bound_ctrl:1
	v_add_f32_dpp v188, v188, v188 row_half_mirror row_mask:0xf bank_mask:0xf bound_ctrl:1
	v_add_f32_dpp v192, v192, v192 row_half_mirror row_mask:0xf bank_mask:0xf bound_ctrl:1
	s_mov_b64 s[42:43], exec
	s_mov_b32 s20, 0x01010101
	s_mov_b32 exec_lo, s20
	s_mov_b32 exec_hi, s20
	v_add_u32_e32 v0, 64, v102
	v_lshlrev_b32_e32 v0, 2, v0
	v_lshl_add_u64 v[116:117], s[12:13], 0, v[0:1]
	global_atomic_add_f32 v[116:117], v180, off
	v_add_u32_e32 v0, 72, v102
	v_lshlrev_b32_e32 v0, 2, v0
	v_lshl_add_u64 v[116:117], s[12:13], 0, v[0:1]
	global_atomic_add_f32 v[116:117], v184, off
	v_add_u32_e32 v0, 80, v102
	v_lshlrev_b32_e32 v0, 2, v0
	v_lshl_add_u64 v[116:117], s[12:13], 0, v[0:1]
	global_atomic_add_f32 v[116:117], v188, off
	v_add_u32_e32 v0, 88, v102
	v_lshlrev_b32_e32 v0, 2, v0
	v_lshl_add_u64 v[116:117], s[12:13], 0, v[0:1]
	global_atomic_add_f32 v[116:117], v192, off
	s_mov_b64 exec, s[42:43]
.Lrt_a_x_2_0:
	ds_write_b128 v98, v[2:5] offset:4608
	ds_write_b128 v98, v[6:9] offset:4640
	ds_write_b128 v98, v[10:13] offset:4672
	ds_write_b128 v98, v[14:17] offset:4704
	ds_read_b128 v[180:183], v99 offset:4608
	ds_read_b128 v[184:187], v99 offset:5760
	ds_read_b128 v[188:191], v99 offset:6912
	ds_read_b128 v[192:195], v99 offset:8064
	v_add_u32_e32 v115, 64, v102
	v_subrev_co_u32_e32 v103, vcc, 0x1000, v115
	v_lshrrev_b32_e32 v103, 11, v103
	v_add_u32_e32 v103, 1, v103
	s_nop 0
	v_cndmask_b32_e64 v103, v103, 0, vcc
	v_add_u32_e32 v0, s48, v103
	v_mul_u32_u24_e32 v0, 0x6000, v0
	v_add_u32_e32 v0, v0, v101
	v_lshl_add_u64 v[116:117], s[50:51], 0, v[0:1]
	global_load_dwordx4 v[212:215], v[116:117], off offset:128
	v_lshlrev_b32_e32 v0, 12, v115
	v_add_u32_e32 v0, v0, v101
	v_lshl_add_u64 v[104:105], s[6:7], 0, v[0:1]
	global_load_dwordx4 v[196:199], v[104:105], off offset:128
	s_and_b64 vcc, exec, s[54:55]
	s_cbranch_vccz .Lrt_a_a_2_1_0
	v_add_u32_e32 v0, s52, v103
	v_mul_u32_u24_e32 v0, 0x6000, v0
	v_add_u32_e32 v0, v0, v101
	v_lshl_add_u64 v[116:117], s[46:47], 0, v[0:1]
	global_load_dwordx4 v[138:141], v[116:117], off offset:128
.Lrt_a_a_2_1_0:
	v_add_u32_e32 v115, 72, v102
	v_subrev_co_u32_e32 v103, vcc, 0x1000, v115
	v_lshrrev_b32_e32 v103, 11, v103
	v_add_u32_e32 v103, 1, v103
	s_nop 0
	v_cndmask_b32_e64 v103, v103, 0, vcc
	v_add_u32_e32 v0, s48, v103
	v_mul_u32_u24_e32 v0, 0x6000, v0
	v_add_u32_e32 v0, v0, v101
	v_lshl_add_u64 v[116:117], s[50:51], 0, v[0:1]
	global_load_dwordx4 v[216:219], v[116:117], off offset:128
	v_lshlrev_b32_e32 v0, 12, v115
	v_add_u32_e32 v0, v0, v101
	v_lshl_add_u64 v[106:107], s[6:7], 0, v[0:1]
	global_load_dwordx4 v[200:203], v[106:107], off offset:128
	s_and_b64 vcc, exec, s[54:55]
	s_cbranch_vccz .Lrt_a_a_2_1_1
	v_add_u32_e32 v0, s52, v103
	v_mul_u32_u24_e32 v0, 0x6000, v0
	v_add_u32_e32 v0, v0, v101
	v_lshl_add_u64 v[116:117], s[46:47], 0, v[0:1]
	global_load_dwordx4 v[142:145], v[116:117], off offset:128
.Lrt_a_a_2_1_1:
	v_add_u32_e32 v115, 80, v102
	v_subrev_co_u32_e32 v103, vcc, 0x1000, v115
	v_lshrrev_b32_e32 v103, 11, v103
	v_add_u32_e32 v103, 1, v103
	s_nop 0
	v_cndmask_b32_e64 v103, v103, 0, vcc
	v_add_u32_e32 v0, s48, v103
	v_mul_u32_u24_e32 v0, 0x6000, v0
	v_add_u32_e32 v0, v0, v101
	v_lshl_add_u64 v[116:117], s[50:51], 0, v[0:1]
	global_load_dwordx4 v[220:223], v[116:117], off offset:128
	v_lshlrev_b32_e32 v0, 12, v115
	v_add_u32_e32 v0, v0, v101
	v_lshl_add_u64 v[108:109], s[6:7], 0, v[0:1]
	global_load_dwordx4 v[204:207], v[108:109], off offset:128
	s_and_b64 vcc, exec, s[54:55]
	s_cbranch_vccz .Lrt_a_a_2_1_2
	v_add_u32_e32 v0, s52, v103
	v_mul_u32_u24_e32 v0, 0x6000, v0
	v_add_u32_e32 v0, v0, v101
	v_lshl_add_u64 v[116:117], s[46:47], 0, v[0:1]
	global_load_dwordx4 v[146:149], v[116:117], off offset:128
.Lrt_a_a_2_1_2:
	v_add_u32_e32 v115, 88, v102
	v_subrev_co_u32_e32 v103, vcc, 0x1000, v115
	v_lshrrev_b32_e32 v103, 11, v103
	v_add_u32_e32 v103, 1, v103
	s_nop 0
	v_cndmask_b32_e64 v103, v103, 0, vcc
	v_add_u32_e32 v0, s48, v103
	v_mul_u32_u24_e32 v0, 0x6000, v0
	v_add_u32_e32 v0, v0, v101
	v_lshl_add_u64 v[116:117], s[50:51], 0, v[0:1]
	global_load_dwordx4 v[134:137], v[116:117], off offset:128
	v_lshlrev_b32_e32 v0, 12, v115
	v_add_u32_e32 v0, v0, v101
	v_lshl_add_u64 v[110:111], s[6:7], 0, v[0:1]
	global_load_dwordx4 v[208:211], v[110:111], off offset:128
	s_and_b64 vcc, exec, s[54:55]
	s_cbranch_vccz .Lrt_a_a_2_1_3
	v_add_u32_e32 v0, s52, v103
	v_mul_u32_u24_e32 v0, 0x6000, v0
	v_add_u32_e32 v0, v0, v101
	v_lshl_add_u64 v[116:117], s[46:47], 0, v[0:1]
	global_load_dwordx4 v[118:121], v[116:117], off offset:128
.Lrt_a_a_2_1_3:
	s_waitcnt vmcnt(0) lgkmcnt(0)
	v_pk_fma_f32 v[196:197], v[180:181], v[212:213], v[196:197]
	v_pk_fma_f32 v[198:199], v[182:183], v[214:215], v[198:199]
	v_pk_fma_f32 v[200:201], v[184:185], v[216:217], v[200:201]
	v_pk_fma_f32 v[202:203], v[186:187], v[218:219], v[202:203]
	v_pk_fma_f32 v[204:205], v[188:189], v[220:221], v[204:205]
	v_pk_fma_f32 v[206:207], v[190:191], v[222:223], v[206:207]
	v_pk_fma_f32 v[208:209], v[192:193], v[134:135], v[208:209]
	v_pk_fma_f32 v[210:211], v[194:195], v[136:137], v[210:211]
	global_store_dwordx4 v[104:105], v[196:199], off offset:128
	global_store_dwordx4 v[106:107], v[200:203], off offset:128
	global_store_dwordx4 v[108:109], v[204:207], off offset:128
	global_store_dwordx4 v[110:111], v[208:211], off offset:128
	s_and_b64 vcc, exec, s[54:55]
	s_cbranch_vccz .Lrt_a_x_2_1
	v_mul_f32_e32 v180, v196, v196
	v_fmac_f32_e32 v180, v197, v197
	v_fmac_f32_e32 v180, v198, v198
	v_fmac_f32_e32 v180, v199, v199
	v_pk_add_f32 v[138:139], v[138:139], 1.0 op_sel_hi:[1,0]
	v_pk_add_f32 v[140:141], v[140:141], 1.0 op_sel_hi:[1,0]
	v_pk_mul_f32 v[196:197], v[196:197], v[126:127]
	v_pk_mul_f32 v[198:199], v[198:199], v[128:129]
	v_pk_mul_f32 v[196:197], v[196:197], v[138:139]
	v_pk_mul_f32 v[198:199], v[198:199], v[140:141]
	v_cvt_pk_f16_f32 v196, v196, v197
	v_cvt_pk_f16_f32 v197, v198, v199
	v_add_u32_e32 v115, 64, v102
	v_lshlrev_b32_e32 v0, 12, v115
	v_add_u32_e32 v0, v0, v101
	v_lshrrev_b32_e32 v0, 1, v0
	v_lshl_add_u64 v[116:117], s[8:9], 0, v[0:1]
	global_store_dwordx2 v[116:117], v[196:197], off offset:64
	v_mul_f32_e32 v184, v200, v200
	v_fmac_f32_e32 v184, v201, v201
	v_fmac_f32_e32 v184, v202, v202
	v_fmac_f32_e32 v184, v203, v203
	v_pk_add_f32 v[142:143], v[142:143], 1.0 op_sel_hi:[1,0]
	v_pk_add_f32 v[144:145], v[144:145], 1.0 op_sel_hi:[1,0]
	v_pk_mul_f32 v[200:201], v[200:201], v[126:127]
	v_pk_mul_f32 v[202:203], v[202:203], v[128:129]
	v_pk_mul_f32 v[200:201], v[200:201], v[142:143]
	v_pk_mul_f32 v[202:203], v[202:203], v[144:145]
	v_cvt_pk_f16_f32 v200, v200, v201
	v_cvt_pk_f16_f32 v201, v202, v203
	v_add_u32_e32 v115, 72, v102
	v_lshlrev_b32_e32 v0, 12, v115
	v_add_u32_e32 v0, v0, v101
	v_lshrrev_b32_e32 v0, 1, v0
	v_lshl_add_u64 v[116:117], s[8:9], 0, v[0:1]
	global_store_dwordx2 v[116:117], v[200:201], off offset:64
	v_mul_f32_e32 v188, v204, v204
	v_fmac_f32_e32 v188, v205, v205
	v_fmac_f32_e32 v188, v206, v206
	v_fmac_f32_e32 v188, v207, v207
	v_pk_add_f32 v[146:147], v[146:147], 1.0 op_sel_hi:[1,0]
	v_pk_add_f32 v[148:149], v[148:149], 1.0 op_sel_hi:[1,0]
	v_pk_mul_f32 v[204:205], v[204:205], v[126:127]
	v_pk_mul_f32 v[206:207], v[206:207], v[128:129]
	v_pk_mul_f32 v[204:205], v[204:205], v[146:147]
	v_pk_mul_f32 v[206:207], v[206:207], v[148:149]
	v_cvt_pk_f16_f32 v204, v204, v205
	v_cvt_pk_f16_f32 v205, v206, v207
	v_add_u32_e32 v115, 80, v102
	v_lshlrev_b32_e32 v0, 12, v115
	v_add_u32_e32 v0, v0, v101
	v_lshrrev_b32_e32 v0, 1, v0
	v_lshl_add_u64 v[116:117], s[8:9], 0, v[0:1]
	global_store_dwordx2 v[116:117], v[204:205], off offset:64
	v_mul_f32_e32 v192, v208, v208
	v_fmac_f32_e32 v192, v209, v209
	v_fmac_f32_e32 v192, v210, v210
	v_fmac_f32_e32 v192, v211, v211
	v_pk_add_f32 v[118:119], v[118:119], 1.0 op_sel_hi:[1,0]
	v_pk_add_f32 v[120:121], v[120:121], 1.0 op_sel_hi:[1,0]
	v_pk_mul_f32 v[208:209], v[208:209], v[126:127]
	v_pk_mul_f32 v[210:211], v[210:211], v[128:129]
	v_pk_mul_f32 v[208:209], v[208:209], v[118:119]
	v_pk_mul_f32 v[210:211], v[210:211], v[120:121]
	v_cvt_pk_f16_f32 v208, v208, v209
	v_cvt_pk_f16_f32 v209, v210, v211
	v_add_u32_e32 v115, 88, v102
	v_lshlrev_b32_e32 v0, 12, v115
	v_add_u32_e32 v0, v0, v101
	v_lshrrev_b32_e32 v0, 1, v0
	v_lshl_add_u64 v[116:117], s[8:9], 0, v[0:1]
	global_store_dwordx2 v[116:117], v[208:209], off offset:64
	s_nop 1
	v_add_f32_dpp v180, v180, v180 quad_perm:[1,0,3,2] row_mask:0xf bank_mask:0xf bound_ctrl:1
	v_add_f32_dpp v184, v184, v184 quad_perm:[1,0,3,2] row_mask:0xf bank_mask:0xf bound_ctrl:1
	v_add_f32_dpp v188, v188, v188 quad_perm:[1,0,3,2] row_mask:0xf bank_mask:0xf bound_ctrl:1
	v_add_f32_dpp v192, v192, v192 quad_perm:[1,0,3,2] row_mask:0xf bank_mask:0xf bound_ctrl:1
	s_nop 1
	v_add_f32_dpp v180, v180, v180 quad_perm:[2,3,0,1] row_mask:0xf bank_mask:0xf bound_ctrl:1
	v_add_f32_dpp v184, v184, v184 quad_perm:[2,3,0,1] row_mask:0xf bank_mask:0xf bound_ctrl:1
	v_add_f32_dpp v188, v188, v188 quad_perm:[2,3,0,1] row_mask:0xf bank_mask:0xf bound_ctrl:1
	v_add_f32_dpp v192, v192, v192 quad_perm:[2,3,0,1] row_mask:0xf bank_mask:0xf bound_ctrl:1
	s_nop 1
	v_add_f32_dpp v180, v180, v180 row_half_mirror row_mask:0xf bank_mask:0xf bound_ctrl:1
	v_add_f32_dpp v184, v184, v184 row_half_mirror row_mask:0xf bank_mask:0xf bound_ctrl:1
	v_add_f32_dpp v188, v188, v188 row_half_mirror row_mask:0xf bank_mask:0xf bound_ctrl:1
	v_add_f32_dpp v192, v192, v192 row_half_mirror row_mask:0xf bank_mask:0xf bound_ctrl:1
	s_mov_b64 s[42:43], exec
	s_mov_b32 s20, 0x01010101
	s_mov_b32 exec_lo, s20
	s_mov_b32 exec_hi, s20
	v_add_u32_e32 v0, 64, v102
	v_lshlrev_b32_e32 v0, 2, v0
	v_lshl_add_u64 v[116:117], s[12:13], 0, v[0:1]
	global_atomic_add_f32 v[116:117], v180, off
	v_add_u32_e32 v0, 72, v102
	v_lshlrev_b32_e32 v0, 2, v0
	v_lshl_add_u64 v[116:117], s[12:13], 0, v[0:1]
	global_atomic_add_f32 v[116:117], v184, off
	v_add_u32_e32 v0, 80, v102
	v_lshlrev_b32_e32 v0, 2, v0
	v_lshl_add_u64 v[116:117], s[12:13], 0, v[0:1]
	global_atomic_add_f32 v[116:117], v188, off
	v_add_u32_e32 v0, 88, v102
	v_lshlrev_b32_e32 v0, 2, v0
	v_lshl_add_u64 v[116:117], s[12:13], 0, v[0:1]
	global_atomic_add_f32 v[116:117], v192, off
	s_mov_b64 exec, s[42:43]
